# hg_h3: gate-row loads of the output epilogue issued together up front; item prologue issues value/gate/query loads before the chunk-state loads so only one round trip is waited
# speedup vs baseline: 1.0084x; 1.0034x over previous
.LBB0_1511:
	s_lshl_b32 s6, s10, 4
	s_ashr_i32 s11, s10, 31
	s_and_b32 s8, s6, 0xffffffc0
	s_lshl_b64 s[6:7], s[10:11], 16
	v_lshl_add_u64 v[108:109], v[98:99], 0, s[6:7]
	s_lshl_b32 s6, s10, 7
	v_add_u32_e32 v66, s8, v146
	v_mov_b64_e32 v[70:71], s[0:1]
	s_and_b32 s11, s6, 0x180
	v_mad_i64_i32 v[66:67], s[6:7], v66, s37, v[70:71]
	v_readlane_b32 s6, v252, 27
	v_readlane_b32 s7, v252, 28
	s_mov_b32 s13, s7
	s_lshl_b32 s12, s11, 1
	v_readlane_b32 s3, v253, 15
	v_lshl_add_u64 v[66:67], v[66:67], 0, s[12:13]
	s_or_b32 s14, s8, s3
	v_lshl_add_u64 v[66:67], v[66:67], 0, v[0:1]
	s_movk_i32 s3, 0x2000
	v_add_co_u32_e32 v66, vcc, s3, v66
	v_addc_co_u32_e32 v67, vcc, 0, v67, vcc
	global_load_dwordx4 v[240:243], v[66:67], off
	v_mov_b32_e32 v107, v1
	v_add_u32_e32 v66, s8, v147
	v_mad_i64_i32 v[66:67], s[6:7], v66, s37, v[70:71]
	v_lshl_add_u64 v[66:67], v[66:67], 0, s[12:13]
	v_lshl_add_u64 v[66:67], v[66:67], 0, v[0:1]
	v_add_co_u32_e32 v66, vcc, s3, v66
	s_movk_i32 s3, 0x1000
	s_nop 0
	v_addc_co_u32_e32 v67, vcc, 0, v67, vcc
	global_load_dwordx4 v[244:247], v[66:67], off
	v_or_b32_e32 v66, s14, v101
	v_mad_i64_i32 v[66:67], s[6:7], v66, s37, v[70:71]
	v_readlane_b32 s6, v254, 46
	v_readlane_b32 s7, v254, 47
	s_mov_b32 s7, s13
	s_mov_b32 s8, s6
	v_lshl_add_u64 v[68:69], v[66:67], 0, s[6:7]
	v_lshl_add_u64 v[68:69], v[68:69], 0, s[12:13]
	v_lshl_add_u64 v[68:69], v[68:69], 0, v[106:107]
	s_mov_b64 s[6:7], 0x1800
	v_lshl_add_u64 v[70:71], v[68:69], 0, s[6:7]
	v_add_co_u32_e32 v68, vcc, s3, v68
	v_writelane_b32 v252, s12, 27
	s_nop 0
	v_addc_co_u32_e32 v69, vcc, 0, v69, vcc
	v_lshl_add_u64 v[66:67], v[66:67], 0, s[12:13]
	v_lshl_add_u64 v[66:67], v[66:67], 0, v[106:107]
	s_mov_b64 s[6:7], 0x2400
	v_lshl_add_u64 v[74:75], v[66:67], 0, s[6:7]
	v_add_co_u32_e32 v66, vcc, 0x2000, v66
	global_load_dwordx4 v[94:97], v[68:69], off offset:2048
	global_load_dwordx4 v[82:85], v[70:71], off offset:48
	global_load_dwordx4 v[86:89], v[70:71], off offset:32
	global_load_dwordx4 v[90:93], v[70:71], off offset:16
	v_addc_co_u32_e32 v67, vcc, 0, v67, vcc
	global_load_dwordx4 v[78:81], v[66:67], off offset:1024
	s_nop 0
	global_load_dwordx4 v[66:69], v[74:75], off offset:48
	global_load_dwordx4 v[70:73], v[74:75], off offset:32
	s_nop 0
	global_load_dwordx4 v[74:77], v[74:75], off offset:16
	v_writelane_b32 v254, s8, 46
	v_writelane_b32 v252, s13, 28
	s_mov_b64 s[6:7], -1
	v_writelane_b32 v254, s9, 47
	v_readlane_b32 s8, v252, 35
	v_readlane_b32 s9, v252, 36
	s_and_b64 vcc, exec, s[8:9]
	global_load_dwordx4 v[18:21], v[108:109], off
	global_load_dwordx4 v[22:25], v[108:109], off offset:256
	global_load_dwordx4 v[26:29], v[108:109], off offset:512
	global_load_dwordx4 v[30:33], v[108:109], off offset:768
	global_load_dwordx4 v[34:37], v[108:109], off offset:1024
	global_load_dwordx4 v[38:41], v[108:109], off offset:1280
	global_load_dwordx4 v[42:45], v[108:109], off offset:1536
	global_load_dwordx4 v[2:5], v[108:109], off offset:1792
	global_load_dwordx4 v[14:17], v[108:109], off offset:16
	global_load_dwordx4 v[46:49], v[108:109], off offset:272
	global_load_dwordx4 v[50:53], v[108:109], off offset:528
	global_load_dwordx4 v[54:57], v[108:109], off offset:784
	global_load_dwordx4 v[58:61], v[108:109], off offset:1040
	global_load_dwordx4 v[62:65], v[108:109], off offset:1296
	global_load_dwordx4 v[6:9], v[108:109], off offset:1552
	global_load_dwordx4 v[10:13], v[108:109], off offset:1808
	s_barrier
	s_waitcnt vmcnt(25)
	ds_write_b128 v148, v[240:243] offset:34816
	s_waitcnt vmcnt(24)
	ds_write_b128 v149, v[244:247] offset:34816
	s_waitcnt vmcnt(23)
	v_lshlrev_b32_e32 v111, 16, v94
	s_cbranch_vccz .LBB0_1513
	s_nop 0
	v_add_f32_dpp v107, v111, v111 row_shl:1 row_mask:0xf bank_mask:0xf bound_ctrl:1
	s_mov_b64 s[6:7], 0
	s_nop 0
	v_add_f32_dpp v107, v107, v107 row_shl:2 row_mask:0xf bank_mask:0xf bound_ctrl:1
	s_nop 1
	v_add_f32_dpp v107, v107, v107 row_shl:4 row_mask:0xf bank_mask:0xf bound_ctrl:1
	s_nop 1
	v_mov_b32_dpp v110, v107 row_shl:8 row_mask:0xf bank_mask:0xf bound_ctrl:1

.LBB0_1589:
	s_or_b64 exec, exec, s[12:13]
	v_add_f32_e32 v115, v115, v116
	v_sub_f32_e32 v115, v115, v114
	v_exp_f32_e32 v114, v114
	v_exp_f32_e32 v115, v115
	v_add_f32_e32 v133, v134, v135
	v_add_f32_e32 v131, v131, v132
	v_add_f32_e32 v127, v127, v128
	v_add_f32_e32 v124, v124, v125
	v_add_f32_e32 v121, v121, v122
	v_add_f32_e32 v118, v118, v119
	v_sub_f32_e32 v160, 1.0, v114
	v_add_f32_e32 v112, v112, v113
	v_sub_f32_e32 v133, v133, v130
	v_sub_f32_e32 v131, v131, v129
	v_exp_f32_e32 v129, v129
	v_sub_f32_e32 v127, v127, v126
	v_exp_f32_e32 v126, v126
	v_sub_f32_e32 v124, v124, v123
	v_exp_f32_e32 v123, v123
	v_sub_f32_e32 v121, v121, v120
	v_exp_f32_e32 v120, v120
	v_sub_f32_e32 v118, v118, v117
	v_exp_f32_e32 v117, v117
	v_mul_f32_e32 v114, v160, v115
	v_exp_f32_e32 v115, v111
	v_sub_f32_e32 v111, v112, v111
	v_exp_f32_e32 v112, v130
	v_exp_f32_e32 v131, v131
	v_exp_f32_e32 v127, v127
	v_exp_f32_e32 v124, v124
	v_exp_f32_e32 v121, v121
	v_exp_f32_e32 v118, v118
	v_exp_f32_e32 v111, v111
	v_exp_f32_e32 v113, v133
	v_sub_f32_e32 v177, 1.0, v129
	v_sub_f32_e32 v175, 1.0, v126
	v_sub_f32_e32 v176, 1.0, v123
	v_sub_f32_e32 v159, 1.0, v120
	v_sub_f32_e32 v174, 1.0, v117
	v_sub_f32_e32 v161, 1.0, v115
	v_sub_f32_e32 v158, 1.0, v112
	v_mul_f32_e32 v128, v177, v131
	v_mul_f32_e32 v126, v175, v127
	v_mul_f32_e32 v122, v176, v124
	v_mul_f32_e32 v120, v159, v121
	v_mul_f32_e32 v116, v174, v118
	v_mul_f32_e32 v115, v161, v111
	v_mul_f32_e32 v117, v158, v113
	v_cvt_pk_bf16_f32 v112, v115, v114
	v_cvt_pk_bf16_f32 v113, v116, v120
	v_cvt_pk_bf16_f32 v114, v122, v126
	v_cvt_pk_bf16_f32 v115, v128, v117
	ds_write_b128 v151, v[112:115]
	s_waitcnt vmcnt(20)
	v_lshlrev_b32_e32 v111, 16, v90
	s_and_b64 vcc, exec, s[6:7]
	s_mov_b64 s[12:13], -1
	s_cbranch_vccnz .LBB0_1593
	v_add_f32_dpp v112, v111, v111 row_shl:1 row_mask:0xf bank_mask:0xf bound_ctrl:1
	s_nop 1
	v_add_f32_dpp v112, v112, v112 row_shl:2 row_mask:0xf bank_mask:0xf bound_ctrl:1
	s_nop 1
	v_add_f32_dpp v114, v112, v112 row_shl:4 row_mask:0xf bank_mask:0xf bound_ctrl:1
	s_nop 1
	v_mov_b32_dpp v115, v114 row_shl:8 row_mask:0xf bank_mask:0xf bound_ctrl:1
	s_cbranch_execnz .LBB0_1595
	s_branch .LBB0_1594

.LBB0_1829:
	s_or_b64 exec, exec, s[6:7]
	v_add_f32_e32 v110, v111, v112
	v_exp_f32_e32 v111, v107
	v_sub_f32_e32 v220, v110, v140
	s_waitcnt vmcnt(19)
	v_lshlrev_b32_e32 v110, 16, v78
	v_exp_f32_e32 v112, v141
	v_mul_f32_e32 v110, v111, v110
	v_exp_f32_e32 v111, v94
	v_and_b32_e32 v78, 0xffff0000, v78
	v_add_f32_e32 v85, v113, v114
	v_sub_f32_e32 v85, v85, v83
	v_mul_f32_e32 v111, v111, v78
	v_lshlrev_b32_e32 v78, 16, v79
	v_mul_f32_e32 v112, v112, v78
	v_and_b32_e32 v78, 0xffff0000, v79
	v_exp_f32_e32 v79, v95
	v_exp_f32_e32 v83, v83
	v_exp_f32_e32 v85, v85
	v_readlane_b32 s8, v253, 18
	v_mul_f32_e32 v113, v79, v78
	v_exp_f32_e32 v79, v156
	v_lshlrev_b32_e32 v78, 16, v80
	v_sub_f32_e32 v83, 1.0, v83
	v_mul_f32_e32 v85, v83, v85
	v_mul_f32_e32 v114, v79, v78
	v_exp_f32_e32 v79, v96
	v_and_b32_e32 v78, 0xffff0000, v80
	v_max_f32_e64 v80, -v178, -v178
	v_min_f32_e32 v80, 0x42f00000, v80
	v_mul_f32_e32 v115, v79, v78
	v_exp_f32_e32 v79, v157
	v_lshlrev_b32_e32 v78, 16, v81
	v_exp_f32_e32 v80, v80
	v_readlane_b32 s9, v253, 19
	v_mul_f32_e32 v116, v79, v78
	v_exp_f32_e32 v79, v97
	v_and_b32_e32 v78, 0xffff0000, v81
	v_max_f32_e64 v81, -v93, -v93
	v_min_f32_e32 v81, 0x42f00000, v81
	v_mul_f32_e32 v117, v79, v78
	v_exp_f32_e32 v79, v178
	s_waitcnt vmcnt(0)
	v_lshlrev_b32_e32 v78, 16, v74
	v_and_b32_e32 v74, 0xffff0000, v74
	v_exp_f32_e32 v81, v81
	v_mul_f32_e32 v118, v79, v78
	v_exp_f32_e32 v78, v90
	v_mul_f32_e32 v80, v185, v80
	v_mul_f32_e32 v81, v182, v81
	s_andn2_b64 vcc, exec, s[8:9]
	v_mul_f32_e32 v119, v78, v74
	v_exp_f32_e32 v78, v179
	v_lshlrev_b32_e32 v74, 16, v75
	v_mul_f32_e32 v120, v78, v74
	v_and_b32_e32 v74, 0xffff0000, v75
	v_exp_f32_e32 v75, v91
	s_nop 0
	v_mul_f32_e32 v121, v75, v74
	v_exp_f32_e32 v75, v180
	v_lshlrev_b32_e32 v74, 16, v76
	v_mul_f32_e32 v122, v75, v74
	v_exp_f32_e32 v75, v92
	v_and_b32_e32 v74, 0xffff0000, v76
	v_max_f32_e64 v76, -v190, -v190
	v_min_f32_e32 v76, 0x42f00000, v76
	v_mul_f32_e32 v123, v75, v74
	v_exp_f32_e32 v75, v181
	v_lshlrev_b32_e32 v74, 16, v77
	v_exp_f32_e32 v76, v76
	v_mul_f32_e32 v126, v75, v74
	v_exp_f32_e32 v75, v93
	v_and_b32_e32 v74, 0xffff0000, v77
	v_max_f32_e64 v77, -v89, -v89
	v_min_f32_e32 v77, 0x42f00000, v77
	v_mul_f32_e32 v127, v75, v74
	v_exp_f32_e32 v75, v190
	v_lshlrev_b32_e32 v74, 16, v70
	v_and_b32_e32 v70, 0xffff0000, v70
	v_exp_f32_e32 v77, v77
	v_mul_f32_e32 v124, v75, v74
	v_exp_f32_e32 v74, v86
	v_mul_f32_e32 v76, v197, v76
	v_mul_f32_e32 v77, v194, v77
	v_mul_f32_e32 v125, v74, v70
	v_exp_f32_e32 v74, v191
	v_lshlrev_b32_e32 v70, 16, v71
	v_mul_f32_e32 v128, v74, v70
	v_and_b32_e32 v70, 0xffff0000, v71
	v_exp_f32_e32 v71, v87
	s_nop 0
	v_mul_f32_e32 v129, v71, v70
	v_exp_f32_e32 v71, v192
	v_lshlrev_b32_e32 v70, 16, v72
	v_mul_f32_e32 v130, v71, v70
	v_exp_f32_e32 v71, v88
	v_and_b32_e32 v70, 0xffff0000, v72
	v_mul_f32_e32 v131, v71, v70
	v_exp_f32_e32 v71, v193
	v_lshlrev_b32_e32 v70, 16, v73
	v_mul_f32_e32 v132, v71, v70
	v_exp_f32_e32 v71, v89
	v_and_b32_e32 v70, 0xffff0000, v73
	v_max_f32_e64 v89, -v97, -v97
	v_min_f32_e32 v89, 0x42f00000, v89
	v_mul_f32_e32 v133, v71, v70
	v_exp_f32_e32 v71, v205
	v_lshlrev_b32_e32 v70, 16, v66
	v_and_b32_e32 v66, 0xffff0000, v66
	v_exp_f32_e32 v89, v89
	v_mul_f32_e32 v134, v71, v70
	v_exp_f32_e32 v70, v208
	v_max_f32_e64 v71, -v235, -v235
	v_min_f32_e32 v71, 0x42f00000, v71
	v_exp_f32_e32 v71, v71
	v_mul_f32_e32 v135, v70, v66
	v_exp_f32_e32 v70, v210
	v_lshlrev_b32_e32 v66, 16, v67
	v_mul_f32_e32 v89, v158, v89
	v_mul_f32_e32 v136, v70, v66
	v_and_b32_e32 v66, 0xffff0000, v67
	v_exp_f32_e32 v67, v227
	v_exp_f32_e32 v70, v236
	v_mul_f32_e32 v137, v67, v66
	v_exp_f32_e32 v67, v231
	v_lshlrev_b32_e32 v66, 16, v68
	v_mul_f32_e32 v138, v67, v66
	v_exp_f32_e32 v67, v235
	v_and_b32_e32 v66, 0xffff0000, v68
	v_mul_f32_e32 v139, v67, v66
	v_exp_f32_e32 v66, v140
	v_lshlrev_b32_e32 v67, 16, v69
	v_mul_f32_e32 v140, v70, v67
	v_max_f32_e64 v67, -v236, -v236
	v_min_f32_e32 v67, 0x42f00000, v67
	v_sub_f32_e32 v68, 1.0, v66
	v_exp_f32_e32 v66, v220
	v_exp_f32_e32 v67, v67
	v_exp_f32_e32 v70, v232
	v_and_b32_e32 v69, 0xffff0000, v69
	v_mul_f32_e32 v66, v68, v66
	v_mul_f32_e32 v67, v68, v67
	v_add_f32_e32 v68, v233, v234
	v_sub_f32_e32 v68, v68, v232
	v_exp_f32_e32 v68, v68
	v_sub_f32_e32 v70, 1.0, v70
	v_mul_f32_e32 v162, v70, v71
	v_exp_f32_e32 v71, v228
	v_mul_f32_e32 v68, v70, v68
	v_add_f32_e32 v70, v229, v230
	v_sub_f32_e32 v70, v70, v228
	v_exp_f32_e32 v70, v70
	v_sub_f32_e32 v71, 1.0, v71
	v_cvt_pk_bf16_f32 v85, v66, v85
	v_cvt_pk_bf16_f32 v66, v110, v111
	v_mul_f32_e32 v163, v71, v70
	v_max_f32_e64 v70, -v231, -v231
	v_min_f32_e32 v70, 0x42f00000, v70
	v_exp_f32_e32 v70, v70
	s_nop 0
	v_mul_f32_e32 v164, v71, v70
	v_add_f32_e32 v70, v225, v226
	v_sub_f32_e32 v70, v70, v224
	v_exp_f32_e32 v71, v224
	v_exp_f32_e32 v70, v70
	v_sub_f32_e32 v71, 1.0, v71
	v_mul_f32_e32 v165, v71, v70
	v_max_f32_e64 v70, -v227, -v227
	v_min_f32_e32 v70, 0x42f00000, v70
	v_exp_f32_e32 v70, v70
	s_nop 0
	v_mul_f32_e32 v166, v71, v70
	v_add_f32_e32 v70, v211, v219
	v_sub_f32_e32 v70, v70, v209
	v_exp_f32_e32 v71, v209
	v_exp_f32_e32 v70, v70
	v_sub_f32_e32 v71, 1.0, v71
	v_mul_f32_e32 v167, v71, v70
	v_max_f32_e64 v70, -v210, -v210
	v_min_f32_e32 v70, 0x42f00000, v70
	v_exp_f32_e32 v70, v70
	s_nop 0
	v_mul_f32_e32 v168, v71, v70
	v_add_f32_e32 v70, v206, v207
	v_sub_f32_e32 v70, v70, v82
	v_exp_f32_e32 v71, v82
	v_exp_f32_e32 v70, v70
	v_sub_f32_e32 v71, 1.0, v71
	v_mul_f32_e32 v82, v71, v70
	v_max_f32_e64 v70, -v208, -v208
	v_min_f32_e32 v70, 0x42f00000, v70
	v_exp_f32_e32 v70, v70
	s_nop 0
	v_mul_f32_e32 v169, v71, v70
	v_add_f32_e32 v70, v203, v204
	v_sub_f32_e32 v70, v70, v202
	v_exp_f32_e32 v71, v202
	v_exp_f32_e32 v70, v70
	v_sub_f32_e32 v71, 1.0, v71
	v_mul_f32_e32 v170, v71, v70
	v_max_f32_e64 v70, -v205, -v205
	v_min_f32_e32 v70, 0x42f00000, v70
	v_exp_f32_e32 v70, v70
	v_cvt_pk_bf16_f32 v82, v170, v82
	v_mul_f32_e32 v171, v71, v70
	v_max_f32_e64 v70, -v193, -v193
	v_min_f32_e32 v70, 0x42f00000, v70
	v_exp_f32_e32 v70, v70
	s_nop 0
	v_mul_f32_e32 v73, v201, v70
	v_max_f32_e64 v70, -v88, -v88
	v_min_f32_e32 v70, 0x42f00000, v70
	v_exp_f32_e32 v70, v70
	v_cvt_pk_bf16_f32 v73, v73, v77
	v_max_f32_e64 v88, -v107, -v107
	v_min_f32_e32 v88, 0x42f00000, v88
	v_mul_f32_e32 v72, v199, v70
	v_max_f32_e64 v70, -v192, -v192
	v_min_f32_e32 v70, 0x42f00000, v70
	v_exp_f32_e32 v70, v70
	v_exp_f32_e32 v88, v88
	v_add_u32_e32 v107, 0xe000, v153
	v_mul_f32_e32 v74, v200, v70
	v_max_f32_e64 v70, -v87, -v87
	v_min_f32_e32 v70, 0x42f00000, v70
	v_exp_f32_e32 v70, v70
	v_cvt_pk_bf16_f32 v72, v74, v72
	v_max_f32_e64 v74, -v181, -v181
	v_min_f32_e32 v74, 0x42f00000, v74
	v_mul_f32_e32 v71, v195, v70
	v_max_f32_e64 v70, -v191, -v191
	v_min_f32_e32 v70, 0x42f00000, v70
	v_exp_f32_e32 v70, v70
	v_exp_f32_e32 v74, v74
	v_mul_f32_e32 v88, v161, v88
	v_mul_f32_e32 v75, v198, v70
	v_max_f32_e64 v70, -v86, -v86
	v_min_f32_e32 v70, 0x42f00000, v70
	v_mul_f32_e32 v77, v189, v74
	v_max_f32_e64 v74, -v92, -v92
	v_exp_f32_e32 v70, v70
	v_min_f32_e32 v74, 0x42f00000, v74
	v_exp_f32_e32 v74, v74
	v_cvt_pk_bf16_f32 v71, v75, v71
	v_mul_f32_e32 v70, v196, v70
	v_cvt_pk_bf16_f32 v70, v76, v70
	v_mul_f32_e32 v76, v187, v74
	v_max_f32_e64 v74, -v180, -v180
	v_min_f32_e32 v74, 0x42f00000, v74
	v_exp_f32_e32 v74, v74
	v_cvt_pk_bf16_f32 v77, v77, v81
	v_mul_f32_e32 v78, v188, v74
	v_max_f32_e64 v74, -v91, -v91
	v_min_f32_e32 v74, 0x42f00000, v74
	v_exp_f32_e32 v74, v74
	v_cvt_pk_bf16_f32 v76, v78, v76
	v_max_f32_e64 v78, -v157, -v157
	v_min_f32_e32 v78, 0x42f00000, v78
	v_mul_f32_e32 v75, v183, v74
	v_max_f32_e64 v74, -v179, -v179
	v_min_f32_e32 v74, 0x42f00000, v74
	v_exp_f32_e32 v74, v74
	v_exp_f32_e32 v78, v78
	v_mul_f32_e32 v79, v186, v74
	v_max_f32_e64 v74, -v90, -v90
	v_min_f32_e32 v74, 0x42f00000, v74
	v_mul_f32_e32 v81, v177, v78
	v_max_f32_e64 v78, -v96, -v96
	v_exp_f32_e32 v74, v74
	v_min_f32_e32 v78, 0x42f00000, v78
	v_exp_f32_e32 v78, v78
	v_cvt_pk_bf16_f32 v75, v79, v75
	v_mul_f32_e32 v74, v184, v74
	v_cvt_pk_bf16_f32 v74, v80, v74
	v_mul_f32_e32 v80, v175, v78
	v_max_f32_e64 v78, -v156, -v156
	v_min_f32_e32 v78, 0x42f00000, v78
	v_exp_f32_e32 v78, v78
	v_cvt_pk_bf16_f32 v81, v81, v89
	v_add_u32_e32 v156, 0xe000, v154
	v_mul_f32_e32 v86, v176, v78
	v_max_f32_e64 v78, -v95, -v95
	v_min_f32_e32 v78, 0x42f00000, v78
	v_exp_f32_e32 v78, v78
	v_cvt_pk_bf16_f32 v80, v86, v80
	v_exp_f32_e32 v86, v84
	v_mul_f32_e32 v79, v159, v78
	v_max_f32_e64 v78, -v141, -v141
	v_min_f32_e32 v78, 0x42f00000, v78
	v_exp_f32_e32 v78, v78
	v_mul_f32_e32 v141, v86, v69
	v_max_f32_e64 v69, -v84, -v84
	v_min_f32_e32 v69, 0x42f00000, v69
	v_exp_f32_e32 v69, v69
	v_mul_f32_e32 v87, v174, v78
	v_max_f32_e64 v78, -v94, -v94
	v_min_f32_e32 v78, 0x42f00000, v78
	v_exp_f32_e32 v78, v78
	v_mul_f32_e32 v69, v83, v69
	v_cvt_pk_bf16_f32 v83, v167, v165
	v_cvt_pk_bf16_f32 v84, v163, v68
	ds_write_b128 v151, v[82:85] offset:48
	v_cvt_pk_bf16_f32 v85, v67, v69
	v_cvt_pk_bf16_f32 v67, v112, v113
	v_cvt_pk_bf16_f32 v68, v114, v115
	v_cvt_pk_bf16_f32 v69, v116, v117
	v_mul_f32_e32 v78, v160, v78
	v_cvt_pk_bf16_f32 v78, v88, v78
	v_cvt_pk_bf16_f32 v79, v87, v79
	v_cvt_pk_bf16_f32 v82, v171, v169
	v_cvt_pk_bf16_f32 v83, v168, v166
	v_mfma_f32_16x16x32_bf16 v[66:69], v[66:69], v[78:81], 0
	v_cvt_pk_bf16_f32 v78, v118, v119
	v_cvt_pk_bf16_f32 v79, v120, v121
	v_cvt_pk_bf16_f32 v80, v122, v123
	v_cvt_pk_bf16_f32 v81, v126, v127
	v_cvt_pk_bf16_f32 v84, v164, v162
	s_waitcnt lgkmcnt(0)
	v_mfma_f32_16x16x32_bf16 v[66:69], v[78:81], v[74:77], v[66:69]
	v_cvt_pk_bf16_f32 v74, v124, v125
	v_cvt_pk_bf16_f32 v75, v128, v129
	v_cvt_pk_bf16_f32 v76, v130, v131
	v_cvt_pk_bf16_f32 v77, v132, v133
	s_barrier
	s_nop 0
	v_mfma_f32_16x16x32_bf16 v[66:69], v[74:77], v[70:73], v[66:69]
	v_cvt_pk_bf16_f32 v70, v134, v135
	v_cvt_pk_bf16_f32 v71, v136, v137
	v_cvt_pk_bf16_f32 v72, v138, v139
	v_cvt_pk_bf16_f32 v73, v140, v141
	s_nop 1
	v_mfma_f32_16x16x32_bf16 v[66:69], v[70:73], v[82:85], v[66:69]
	s_nop 7
	v_cndmask_b32_e64 v66, 0, v66, s[44:45]
	ds_write_b32 v152, v66 offset:57344
	v_cndmask_b32_e64 v66, 0, v67, s[46:47]
	v_cndmask_b32_e64 v67, 0, v68, s[48:49]
	ds_write2_b32 v107, v66, v67 offset1:20
	v_cndmask_b32_e64 v66, 0, v69, s[50:51]
	ds_write_b32 v153, v66 offset:57504
	s_waitcnt lgkmcnt(0)
	ds_read_b128 v[66:69], v150 offset:34816
	ds_read2_b32 v[96:97], v156 offset1:4
	ds_read2_b32 v[86:87], v156 offset0:8 offset1:12
	ds_read_b128 v[162:165], v150 offset:35968
	s_waitcnt lgkmcnt(3)
	v_lshlrev_b32_e32 v70, 16, v66
	v_and_b32_e32 v71, 0xffff0000, v66
	v_lshlrev_b32_e32 v74, 16, v67
	v_and_b32_e32 v78, 0xffff0000, v67
	v_lshlrev_b32_e32 v82, 16, v68
	v_and_b32_e32 v88, 0xffff0000, v68
	v_lshlrev_b32_e32 v92, 16, v69
	v_and_b32_e32 v157, 0xffff0000, v69
	s_waitcnt lgkmcnt(2)
	v_mfma_f32_16x16x4_f32 v[66:69], v96, v70, 0
	s_waitcnt lgkmcnt(0)
	v_lshlrev_b32_e32 v166, 16, v164
	v_and_b32_e32 v164, 0xffff0000, v164
	v_lshlrev_b32_e32 v167, 16, v165
	v_and_b32_e32 v165, 0xffff0000, v165
	v_mfma_f32_16x16x4_f32 v[70:73], v96, v71, 0
	v_mfma_f32_16x16x4_f32 v[74:77], v96, v74, 0
	v_mfma_f32_16x16x4_f32 v[78:81], v96, v78, 0
	v_mfma_f32_16x16x4_f32 v[82:85], v96, v82, 0
	v_mfma_f32_16x16x4_f32 v[88:91], v96, v88, 0
	v_mfma_f32_16x16x4_f32 v[92:95], v96, v92, 0
	v_mfma_f32_16x16x4_f32 v[158:161], v96, v157, 0
	v_lshlrev_b32_e32 v96, 16, v162
	v_and_b32_e32 v157, 0xffff0000, v162
	v_lshlrev_b32_e32 v162, 16, v163
	v_and_b32_e32 v163, 0xffff0000, v163
	v_mfma_f32_16x16x4_f32 v[66:69], v97, v96, v[66:69]
	v_mfma_f32_16x16x4_f32 v[70:73], v97, v157, v[70:73]
	v_mfma_f32_16x16x4_f32 v[74:77], v97, v162, v[74:77]
	v_mfma_f32_16x16x4_f32 v[78:81], v97, v163, v[78:81]
	v_mfma_f32_16x16x4_f32 v[82:85], v97, v166, v[82:85]
	v_mfma_f32_16x16x4_f32 v[88:91], v97, v164, v[88:91]
	v_mfma_f32_16x16x4_f32 v[92:95], v97, v167, v[92:95]
	v_mfma_f32_16x16x4_f32 v[158:161], v97, v165, v[158:161]
	ds_read_b128 v[162:165], v150 offset:37120
	s_waitcnt lgkmcnt(0)
	v_lshlrev_b32_e32 v96, 16, v162
	v_and_b32_e32 v97, 0xffff0000, v162
	v_lshlrev_b32_e32 v157, 16, v163
	v_and_b32_e32 v162, 0xffff0000, v163
	v_lshlrev_b32_e32 v163, 16, v164
	v_and_b32_e32 v164, 0xffff0000, v164
	v_lshlrev_b32_e32 v166, 16, v165
	v_and_b32_e32 v165, 0xffff0000, v165
	v_mfma_f32_16x16x4_f32 v[66:69], v86, v96, v[66:69]
	v_mfma_f32_16x16x4_f32 v[70:73], v86, v97, v[70:73]
	v_mfma_f32_16x16x4_f32 v[74:77], v86, v157, v[74:77]
	v_mfma_f32_16x16x4_f32 v[78:81], v86, v162, v[78:81]
	v_mfma_f32_16x16x4_f32 v[82:85], v86, v163, v[82:85]
	v_mfma_f32_16x16x4_f32 v[88:91], v86, v164, v[88:91]
	v_mfma_f32_16x16x4_f32 v[94:97], v86, v166, v[92:95]
	v_mfma_f32_16x16x4_f32 v[158:161], v86, v165, v[158:161]
	ds_read_b128 v[162:165], v150 offset:38272
	s_waitcnt lgkmcnt(0)
	s_waitcnt lgkmcnt(0)
	v_lshlrev_b32_e32 v86, 16, v162
	v_and_b32_e32 v92, 0xffff0000, v162
	v_lshlrev_b32_e32 v93, 16, v163
	v_and_b32_e32 v157, 0xffff0000, v163
	v_lshlrev_b32_e32 v162, 16, v164
	v_and_b32_e32 v163, 0xffff0000, v164
	v_lshlrev_b32_e32 v164, 16, v165
	v_and_b32_e32 v165, 0xffff0000, v165
	v_mfma_f32_16x16x4_f32 v[66:69], v87, v86, v[66:69]
	v_mfma_f32_16x16x4_f32 v[70:73], v87, v92, v[70:73]
	v_mfma_f32_16x16x4_f32 v[74:77], v87, v93, v[74:77]
	v_mfma_f32_16x16x4_f32 v[78:81], v87, v157, v[78:81]
	v_cndmask_b32_e64 v157, 0, 1, s[8:9]
	v_cmp_ne_u32_e64 s[6:7], 1, v157
	v_mfma_f32_16x16x4_f32 v[82:85], v87, v162, v[82:85]
	v_mfma_f32_16x16x4_f32 v[90:93], v87, v163, v[88:91]
	v_mfma_f32_16x16x4_f32 v[94:97], v87, v164, v[94:97]
	v_mfma_f32_16x16x4_f32 v[86:89], v87, v165, v[158:161]
	s_cbranch_vccnz .LBB0_1836
	s_mov_b32 s8, 0
	s_mov_b32 s9, -1
	s_branch .LBB0_1832

.LBB0_1840:
	v_readlane_b32 s6, v253, 2
	v_readlane_b32 s7, v253, 3
	s_andn2_b64 vcc, exec, s[6:7]
	s_waitcnt lgkmcnt(0)
	s_barrier
	s_cbranch_vccnz .LBB0_1510
	v_readlane_b32 s8, v252, 27
	v_readlane_b32 s9, v252, 28
	s_lshl_b32 s6, s11, 2
	s_mov_b32 s7, s9
	v_add_u32_e32 v44, s14, v142
	v_mov_b64_e32 v[46:47], s[0:1]
	v_lshl_add_u64 v[38:39], v[104:105], 0, s[6:7]
	v_mad_i64_i32 v[40:41], s[6:7], v44, s37, v[46:47]
	v_lshl_add_u64 v[40:41], v[40:41], 0, s[8:9]
	v_lshl_add_u64 v[40:41], v[40:41], 0, v[0:1]
	s_movk_i32 s11, 0x2000
	global_load_dwordx4 v[18:21], v[38:39], off
	v_add_co_u32_e32 v40, vcc, s11, v40
	v_xor_b32_e32 v42, 1, v216
	s_nop 0
	v_addc_co_u32_e32 v41, vcc, 0, v41, vcc
	global_load_dwordx4 v[50:53], v[40:41], off offset:2048
	s_nop 0
	global_load_dwordx4 v[38:41], v[38:39], off offset:16
	v_or_b32_e32 v94, 1, v44
	v_mad_i64_i32 v[92:93], s[6:7], v94, s37, v[46:47]
	v_lshl_add_u64 v[92:93], v[92:93], 0, s[8:9]
	v_lshl_add_u64 v[92:93], v[92:93], 0, v[0:1]
	v_add_co_u32_e32 v92, vcc, s11, v92
	s_nop 1
	v_addc_co_u32_e32 v93, vcc, 0, v93, vcc
	global_load_dwordx4 v[80:83], v[92:93], off offset:2048
	v_or_b32_e32 v94, 2, v44
	v_mad_i64_i32 v[92:93], s[6:7], v94, s37, v[46:47]
	v_lshl_add_u64 v[92:93], v[92:93], 0, s[8:9]
	v_lshl_add_u64 v[92:93], v[92:93], 0, v[0:1]
	v_add_co_u32_e32 v92, vcc, s11, v92
	s_nop 1
	v_addc_co_u32_e32 v93, vcc, 0, v93, vcc
	global_load_dwordx4 v[84:87], v[92:93], off offset:2048
	v_or_b32_e32 v94, 3, v44
	v_mad_i64_i32 v[92:93], s[6:7], v94, s37, v[46:47]
	v_lshl_add_u64 v[92:93], v[92:93], 0, s[8:9]
	v_lshl_add_u64 v[92:93], v[92:93], 0, v[0:1]
	v_add_co_u32_e32 v92, vcc, s11, v92
	s_nop 1
	v_addc_co_u32_e32 v93, vcc, 0, v93, vcc
	global_load_dwordx4 v[88:91], v[92:93], off offset:2048
	ds_read_b128 v[54:57], v155
	ds_read_b128 v[58:61], v155 offset:16
	v_cmp_lt_i32_e32 vcc, v42, v217
	v_mov_b32_e32 v43, v30
	v_mov_b32_e32 v64, v6
	v_cndmask_b32_e32 v42, v216, v42, vcc
	v_lshlrev_b32_e32 v48, 2, v42
	v_mov_b32_e32 v42, v34
	s_waitcnt lgkmcnt(1)
	v_mov_b32_e32 v62, v54
	v_mov_b32_e32 v63, v56
	v_pk_add_f32 v[62:63], v[42:43], v[62:63]
	v_mov_b32_e32 v42, v26
	v_mov_b32_e32 v43, v22
	v_mov_b32_e32 v56, v55
	v_pk_add_f32 v[54:55], v[42:43], v[56:57]
	v_mov_b32_e32 v65, v10
	s_waitcnt lgkmcnt(0)
	v_mov_b32_e32 v66, v58
	v_mov_b32_e32 v67, v60
	v_pk_mul_f32 v[42:43], v[62:63], v[62:63]
	v_pk_mul_f32 v[56:57], v[54:55], v[54:55]
	v_pk_add_f32 v[64:65], v[64:65], v[66:67]
	v_mov_b32_e32 v66, v2
	v_mov_b32_e32 v67, v14
	v_mov_b32_e32 v60, v59
	v_pk_add_f32 v[58:59], v[66:67], v[60:61]
	v_add_f32_e32 v2, v42, v56
	v_mov_b32_e32 v60, v58
	v_mov_b32_e32 v61, v64
	v_add_f32_e32 v2, v43, v2
	v_pk_mul_f32 v[60:61], v[60:61], v[60:61]
	v_add_f32_e32 v2, v57, v2
	v_mov_b32_e32 v66, v59
	v_mov_b32_e32 v67, v65
	v_add_f32_e32 v2, v61, v2
	v_pk_mul_f32 v[66:67], v[66:67], v[66:67]
	v_add_f32_e32 v2, v60, v2
	v_add_f32_e32 v2, v67, v2
	v_add_f32_e32 v6, v66, v2
	ds_bpermute_b32 v10, v48, v6
	v_xor_b32_e32 v2, 2, v216
	v_cmp_lt_i32_e32 vcc, v2, v217
	v_xor_b32_e32 v22, 8, v216
	s_mov_b32 s3, 0xf800000
	v_cndmask_b32_e32 v2, v216, v2, vcc
	v_lshlrev_b32_e32 v2, 2, v2
	s_waitcnt lgkmcnt(0)
	v_add_f32_e32 v10, v6, v10
	ds_bpermute_b32 v14, v2, v10
	v_xor_b32_e32 v6, 4, v216
	v_cmp_lt_i32_e32 vcc, v6, v217
	v_ashrrev_i32_e32 v45, 31, v44
	s_waitcnt lgkmcnt(0)
	v_add_f32_e32 v10, v10, v14
	v_cndmask_b32_e32 v6, v216, v6, vcc
	v_lshlrev_b32_e32 v6, 2, v6
	ds_bpermute_b32 v14, v6, v10
	v_cmp_lt_i32_e32 vcc, v22, v217
	s_waitcnt lgkmcnt(0)
	v_add_f32_e32 v10, v10, v14
	v_cndmask_b32_e32 v22, v216, v22, vcc
	v_lshlrev_b32_e32 v26, 2, v22
	ds_bpermute_b32 v14, v26, v10
	s_waitcnt lgkmcnt(0)
	v_add_f32_e32 v10, v10, v14
	v_fmamk_f32 v10, v10, 0x3c000000, v156
	v_mul_f32_e32 v14, 0x4f800000, v10
	v_cmp_gt_f32_e32 vcc, s3, v10
	s_waitcnt vmcnt(5)
	v_mov_b32_e32 v42, v18
	v_cndmask_b32_e32 v10, v10, v14, vcc
	v_sqrt_f32_e32 v14, v10
	v_mov_b32_e32 v43, v20
	v_mov_b32_e32 v20, v19
	s_waitcnt vmcnt(4)
	v_lshlrev_b32_e32 v19, 16, v51
	v_add_u32_e32 v22, -1, v14
	v_fma_f32 v30, -v22, v14, v10
	v_cmp_ge_f32_e64 s[6:7], 0, v30
	v_add_u32_e32 v30, 1, v14
	v_lshlrev_b32_e32 v18, 16, v50
	v_cndmask_b32_e64 v22, v14, v22, s[6:7]
	v_fma_f32 v14, -v30, v14, v10
	v_cmp_lt_f32_e64 s[6:7], 0, v14
	v_and_b32_e32 v51, 0xffff0000, v51
	v_and_b32_e32 v50, 0xffff0000, v50
	v_cndmask_b32_e64 v14, v22, v30, s[6:7]
	v_mul_f32_e32 v22, 0x37800000, v14
	v_cndmask_b32_e32 v14, v14, v22, vcc
	v_cmp_class_f32_e32 vcc, v10, v157
	v_lshlrev_b32_e32 v57, 16, v53
	v_lshlrev_b32_e32 v56, 16, v52
	v_cndmask_b32_e32 v10, v14, v10, vcc
	v_div_scale_f32 v14, s[6:7], v10, v10, 1.0
	v_rcp_f32_e32 v22, v14
	v_and_b32_e32 v53, 0xffff0000, v53
	v_and_b32_e32 v52, 0xffff0000, v52
	v_fma_f32 v30, -v14, v22, 1.0
	v_fmac_f32_e32 v22, v30, v22
	v_div_scale_f32 v30, vcc, 1.0, v10, 1.0
	v_mul_f32_e32 v34, v30, v22
	v_fma_f32 v49, -v14, v34, v30
	v_fmac_f32_e32 v34, v49, v22
	v_fma_f32 v14, -v14, v34, v30
	v_div_fmas_f32 v14, v14, v22, v34
	v_div_fixup_f32 v10, v14, v10, 1.0
	v_pk_mul_f32 v[60:61], v[62:63], v[10:11] op_sel_hi:[1,0]
	s_nop 0
	v_pk_mul_f32 v[60:61], v[42:43], v[60:61]
	s_nop 0
	v_pk_mul_f32 v[60:61], v[60:61], v[18:19]
	v_pk_mul_f32 v[18:19], v[54:55], v[10:11] op_sel_hi:[1,0]
	v_pk_mul_f32 v[54:55], v[64:65], v[10:11] op_sel_hi:[1,0]
	v_pk_mul_f32 v[18:19], v[20:21], v[18:19]
	v_bfe_u32 v34, v60, 16, 1
	v_pk_mul_f32 v[50:51], v[18:19], v[50:51]
	s_waitcnt vmcnt(3)
	v_mov_b32_e32 v18, v38
	v_mov_b32_e32 v19, v40
	v_pk_mul_f32 v[54:55], v[18:19], v[54:55]
	v_mov_b32_e32 v40, v39
	v_pk_mul_f32 v[54:55], v[54:55], v[56:57]
	v_pk_mul_f32 v[56:57], v[58:59], v[10:11] op_sel_hi:[1,0]
	v_bfe_u32 v22, v51, 16, 1
	v_pk_mul_f32 v[38:39], v[40:41], v[56:57]
	v_add3_u32 v22, v51, v22, s39
	v_pk_mul_f32 v[38:39], v[38:39], v[52:53]
	v_bfe_u32 v49, v55, 16, 1
	v_bfe_u32 v10, v39, 16, 1
	v_bfe_u32 v14, v38, 16, 1
	v_add3_u32 v14, v38, v14, s39
	v_add3_u32 v10, v39, v10, s39
	v_bfe_u32 v38, v61, 16, 1
	v_bfe_u32 v39, v54, 16, 1
	v_add3_u32 v39, v54, v39, s39
	v_add3_u32 v38, v61, v38, s39
	v_lshrrev_b32_e32 v38, 16, v38
	v_lshrrev_b32_e32 v39, 16, v39
	v_and_or_b32 v52, v14, s36, v39
	v_and_or_b32 v51, v22, s36, v38
	v_lshlrev_b64 v[38:39], 12, v[44:45]
	v_bfe_u32 v30, v50, 16, 1
	v_add3_u32 v49, v55, v49, s39
	v_add3_u32 v34, v60, v34, s39
	v_lshl_add_u64 v[38:39], s[4:5], 0, v[38:39]
	v_add3_u32 v30, v50, v30, s39
	v_lshrrev_b32_e32 v34, 16, v34
	v_lshrrev_b32_e32 v49, 16, v49
	v_lshl_add_u64 v[38:39], v[38:39], 0, s[8:9]
	v_and_or_b32 v53, v10, s36, v49
	v_and_or_b32 v50, v30, s36, v34
	v_lshl_add_u64 v[38:39], v[38:39], 0, v[0:1]
	v_or_b32_e32 v34, 1, v44
	global_store_dwordx4 v[38:39], v[50:53], off offset:3072
	v_mad_i64_i32 v[38:39], s[6:7], v34, s37, v[46:47]
	v_lshl_add_u64 v[38:39], v[38:39], 0, s[8:9]
	v_lshl_add_u64 v[38:39], v[38:39], 0, v[0:1]
	v_add_co_u32_e32 v38, vcc, s11, v38
	v_mov_b32_e32 v30, v35
	s_nop 0
	v_addc_co_u32_e32 v39, vcc, 0, v39, vcc
	s_waitcnt vmcnt(3)
	v_mov_b32_e32 v50, v80
	v_mov_b32_e32 v51, v81
	v_mov_b32_e32 v52, v82
	v_mov_b32_e32 v53, v83
	ds_read_b128 v[54:57], v155 offset:512
	ds_read_b128 v[58:61], v155 offset:528
	v_mov_b32_e32 v22, v27
	v_mov_b32_e32 v10, v7
	v_mov_b32_e32 v14, v3
	s_waitcnt lgkmcnt(1)
	v_mov_b32_e32 v38, v54
	v_mov_b32_e32 v39, v56
	v_mov_b32_e32 v56, v55
	v_pk_add_f32 v[30:31], v[30:31], v[38:39]
	v_pk_add_f32 v[22:23], v[22:23], v[56:57]
	v_pk_mul_f32 v[38:39], v[30:31], v[30:31]
	v_pk_mul_f32 v[54:55], v[22:23], v[22:23]
	s_waitcnt lgkmcnt(0)
	v_mov_b32_e32 v56, v58
	v_mov_b32_e32 v57, v60
	v_mov_b32_e32 v60, v59
	v_pk_add_f32 v[10:11], v[10:11], v[56:57]
	v_pk_add_f32 v[14:15], v[14:15], v[60:61]
	v_add_f32_e32 v3, v38, v54
	v_mov_b32_e32 v56, v14
	v_mov_b32_e32 v57, v10
	v_add_f32_e32 v3, v39, v3
	v_pk_mul_f32 v[56:57], v[56:57], v[56:57]
	v_add_f32_e32 v3, v55, v3
	v_mov_b32_e32 v58, v15
	v_mov_b32_e32 v59, v11
	v_add_f32_e32 v3, v57, v3
	v_pk_mul_f32 v[58:59], v[58:59], v[58:59]
	v_add_f32_e32 v3, v56, v3
	v_add_f32_e32 v3, v59, v3
	v_add_f32_e32 v3, v58, v3
	ds_bpermute_b32 v7, v48, v3
	v_ashrrev_i32_e32 v35, 31, v34
	s_waitcnt lgkmcnt(0)
	v_add_f32_e32 v3, v3, v7
	ds_bpermute_b32 v7, v2, v3
	s_waitcnt lgkmcnt(0)
	v_add_f32_e32 v3, v3, v7
	ds_bpermute_b32 v7, v6, v3
	s_waitcnt lgkmcnt(0)
	v_add_f32_e32 v3, v3, v7
	ds_bpermute_b32 v7, v26, v3
	s_waitcnt lgkmcnt(0)
	v_add_f32_e32 v3, v3, v7
	v_fmamk_f32 v3, v3, 0x3c000000, v156
	v_mul_f32_e32 v7, 0x4f800000, v3
	v_cmp_gt_f32_e32 vcc, s3, v3
	v_lshlrev_b32_e32 v39, 16, v51
	v_cndmask_b32_e32 v3, v3, v7, vcc
	v_sqrt_f32_e32 v7, v3
	v_lshlrev_b32_e32 v38, 16, v50
	v_and_b32_e32 v51, 0xffff0000, v51
	v_and_b32_e32 v50, 0xffff0000, v50
	v_add_u32_e32 v27, -1, v7
	v_fma_f32 v45, -v27, v7, v3
	v_cmp_ge_f32_e64 s[6:7], 0, v45
	v_add_u32_e32 v45, 1, v7
	v_lshlrev_b32_e32 v55, 16, v53
	v_cndmask_b32_e64 v27, v7, v27, s[6:7]
	v_fma_f32 v7, -v45, v7, v3
	v_cmp_lt_f32_e64 s[6:7], 0, v7
	v_lshlrev_b32_e32 v54, 16, v52
	v_and_b32_e32 v53, 0xffff0000, v53
	v_cndmask_b32_e64 v7, v27, v45, s[6:7]
	v_mul_f32_e32 v27, 0x37800000, v7
	v_cndmask_b32_e32 v7, v7, v27, vcc
	v_cmp_class_f32_e32 vcc, v3, v157
	v_and_b32_e32 v52, 0xffff0000, v52
	s_nop 0
	v_cndmask_b32_e32 v3, v7, v3, vcc
	v_div_scale_f32 v7, s[6:7], v3, v3, 1.0
	v_rcp_f32_e32 v27, v7
	s_nop 0
	v_fma_f32 v45, -v7, v27, 1.0
	v_fmac_f32_e32 v27, v45, v27
	v_div_scale_f32 v45, vcc, 1.0, v3, 1.0
	v_mul_f32_e32 v49, v45, v27
	v_fma_f32 v56, -v7, v49, v45
	v_fmac_f32_e32 v49, v56, v27
	v_fma_f32 v7, -v7, v49, v45
	v_div_fmas_f32 v7, v7, v27, v49
	v_div_fixup_f32 v56, v7, v3, 1.0
	v_pk_mul_f32 v[22:23], v[22:23], v[56:57] op_sel_hi:[1,0]
	v_pk_mul_f32 v[30:31], v[30:31], v[56:57] op_sel_hi:[1,0]
	v_pk_mul_f32 v[22:23], v[20:21], v[22:23]
	v_pk_mul_f32 v[10:11], v[10:11], v[56:57] op_sel_hi:[1,0]
	v_pk_mul_f32 v[30:31], v[42:43], v[30:31]
	v_pk_mul_f32 v[22:23], v[22:23], v[50:51]
	v_pk_mul_f32 v[10:11], v[18:19], v[10:11]
	v_pk_mul_f32 v[14:15], v[14:15], v[56:57] op_sel_hi:[1,0]
	v_pk_mul_f32 v[30:31], v[30:31], v[38:39]
	v_pk_mul_f32 v[10:11], v[10:11], v[54:55]
	v_pk_mul_f32 v[14:15], v[40:41], v[14:15]
	v_bfe_u32 v27, v23, 16, 1
	v_bfe_u32 v38, v22, 16, 1
	v_pk_mul_f32 v[14:15], v[14:15], v[52:53]
	v_add3_u32 v22, v22, v38, s39
	v_add3_u32 v23, v23, v27, s39
	v_bfe_u32 v27, v10, 16, 1
	v_bfe_u32 v38, v11, 16, 1
	v_bfe_u32 v3, v15, 16, 1
	v_bfe_u32 v7, v14, 16, 1
	v_add3_u32 v11, v11, v38, s39
	v_add3_u32 v10, v10, v27, s39
	v_add3_u32 v7, v14, v7, s39
	v_add3_u32 v3, v15, v3, s39
	v_lshrrev_b32_e32 v10, 16, v10
	v_lshrrev_b32_e32 v11, 16, v11
	v_bfe_u32 v14, v30, 16, 1
	v_bfe_u32 v15, v31, 16, 1
	v_and_or_b32 v53, v3, s36, v11
	v_and_or_b32 v52, v7, s36, v10
	v_lshlrev_b64 v[10:11], 12, v[34:35]
	v_add3_u32 v15, v31, v15, s39
	v_add3_u32 v14, v30, v14, s39
	v_lshl_add_u64 v[10:11], s[4:5], 0, v[10:11]
	v_lshrrev_b32_e32 v14, 16, v14
	v_lshrrev_b32_e32 v15, 16, v15
	v_lshl_add_u64 v[10:11], v[10:11], 0, s[8:9]
	v_and_or_b32 v51, v23, s36, v15
	v_and_or_b32 v50, v22, s36, v14
	v_lshl_add_u64 v[10:11], v[10:11], 0, v[0:1]
	global_store_dwordx4 v[10:11], v[50:53], off offset:3072
	v_or_b32_e32 v10, 2, v44
	v_mad_i64_i32 v[14:15], s[6:7], v10, s37, v[46:47]
	v_lshl_add_u64 v[14:15], v[14:15], 0, s[8:9]
	v_lshl_add_u64 v[14:15], v[14:15], 0, v[0:1]
	v_add_co_u32_e32 v14, vcc, s11, v14
	v_mov_b32_e32 v38, v8
	s_nop 0
	v_addc_co_u32_e32 v15, vcc, 0, v15, vcc
	s_waitcnt vmcnt(3)
	v_mov_b32_e32 v50, v84
	v_mov_b32_e32 v51, v85
	v_mov_b32_e32 v52, v86
	v_mov_b32_e32 v53, v87
	ds_read_b128 v[54:57], v155 offset:1024
	ds_read_b128 v[58:61], v155 offset:1040
	v_mov_b32_e32 v14, v36
	v_mov_b32_e32 v15, v32
	v_mov_b32_e32 v39, v12
	s_waitcnt lgkmcnt(1)
	v_mov_b32_e32 v22, v54
	v_mov_b32_e32 v23, v56
	v_pk_add_f32 v[14:15], v[14:15], v[22:23]
	v_mov_b32_e32 v22, v28
	v_mov_b32_e32 v23, v24
	v_mov_b32_e32 v56, v55
	v_pk_add_f32 v[22:23], v[22:23], v[56:57]
	s_waitcnt lgkmcnt(0)
	v_mov_b32_e32 v54, v58
	v_mov_b32_e32 v55, v60
	v_pk_mul_f32 v[30:31], v[14:15], v[14:15]
	v_pk_mul_f32 v[34:35], v[22:23], v[22:23]
	v_pk_add_f32 v[38:39], v[38:39], v[54:55]
	v_mov_b32_e32 v54, v4
	v_mov_b32_e32 v55, v16
	v_mov_b32_e32 v60, v59
	v_pk_add_f32 v[54:55], v[54:55], v[60:61]
	v_add_f32_e32 v3, v30, v34
	v_mov_b32_e32 v56, v54
	v_mov_b32_e32 v57, v38
	v_add_f32_e32 v3, v31, v3
	v_pk_mul_f32 v[56:57], v[56:57], v[56:57]
	v_add_f32_e32 v3, v35, v3
	v_mov_b32_e32 v58, v55
	v_mov_b32_e32 v59, v39
	v_add_f32_e32 v3, v57, v3
	v_pk_mul_f32 v[58:59], v[58:59], v[58:59]
	v_add_f32_e32 v3, v56, v3
	v_add_f32_e32 v3, v59, v3
	v_add_f32_e32 v3, v58, v3
	ds_bpermute_b32 v4, v48, v3
	v_ashrrev_i32_e32 v11, 31, v10
	v_lshlrev_b64 v[10:11], 12, v[10:11]
	v_lshl_add_u64 v[10:11], s[4:5], 0, v[10:11]
	v_lshl_add_u64 v[10:11], v[10:11], 0, s[8:9]
	s_waitcnt lgkmcnt(0)
	v_add_f32_e32 v3, v3, v4
	ds_bpermute_b32 v4, v2, v3
	v_lshl_add_u64 v[10:11], v[10:11], 0, v[0:1]
	v_mov_b32_e32 v32, v37
	v_mov_b32_e32 v24, v29
	s_waitcnt lgkmcnt(0)
	v_add_f32_e32 v3, v3, v4
	ds_bpermute_b32 v4, v6, v3
	s_waitcnt lgkmcnt(0)
	v_add_f32_e32 v3, v3, v4
	ds_bpermute_b32 v4, v26, v3
	s_waitcnt lgkmcnt(0)
	v_add_f32_e32 v3, v3, v4
	v_fmamk_f32 v3, v3, 0x3c000000, v156
	v_mul_f32_e32 v4, 0x4f800000, v3
	v_cmp_gt_f32_e32 vcc, s3, v3
	v_lshlrev_b32_e32 v31, 16, v51
	v_cndmask_b32_e32 v3, v3, v4, vcc
	v_sqrt_f32_e32 v4, v3
	v_lshlrev_b32_e32 v30, 16, v50
	v_and_b32_e32 v35, 0xffff0000, v51
	v_and_b32_e32 v34, 0xffff0000, v50
	v_add_u32_e32 v7, -1, v4
	v_fma_f32 v8, -v7, v4, v3
	v_cmp_ge_f32_e64 s[6:7], 0, v8
	v_add_u32_e32 v8, 1, v4
	v_lshlrev_b32_e32 v51, 16, v53
	v_cndmask_b32_e64 v7, v4, v7, s[6:7]
	v_fma_f32 v4, -v8, v4, v3
	v_cmp_lt_f32_e64 s[6:7], 0, v4
	v_lshlrev_b32_e32 v50, 16, v52
	v_and_b32_e32 v53, 0xffff0000, v53
	v_cndmask_b32_e64 v4, v7, v8, s[6:7]
	v_mul_f32_e32 v7, 0x37800000, v4
	v_cndmask_b32_e32 v4, v4, v7, vcc
	v_cmp_class_f32_e32 vcc, v3, v157
	v_and_b32_e32 v52, 0xffff0000, v52
	s_nop 0
	v_cndmask_b32_e32 v3, v4, v3, vcc
	v_div_scale_f32 v4, s[6:7], v3, v3, 1.0
	v_rcp_f32_e32 v7, v4
	s_nop 0
	v_fma_f32 v8, -v4, v7, 1.0
	v_fmac_f32_e32 v7, v8, v7
	v_div_scale_f32 v8, vcc, 1.0, v3, 1.0
	v_mul_f32_e32 v12, v8, v7
	v_fma_f32 v16, -v4, v12, v8
	v_fmac_f32_e32 v12, v16, v7
	v_fma_f32 v4, -v4, v12, v8
	v_div_fmas_f32 v4, v4, v7, v12
	v_div_fixup_f32 v4, v4, v3, 1.0
	v_pk_mul_f32 v[14:15], v[14:15], v[4:5] op_sel_hi:[1,0]
	v_pk_mul_f32 v[22:23], v[22:23], v[4:5] op_sel_hi:[1,0]
	v_pk_mul_f32 v[14:15], v[42:43], v[14:15]
	v_pk_mul_f32 v[22:23], v[20:21], v[22:23]
	v_pk_mul_f32 v[14:15], v[14:15], v[30:31]
	v_pk_mul_f32 v[30:31], v[38:39], v[4:5] op_sel_hi:[1,0]
	v_pk_mul_f32 v[22:23], v[22:23], v[34:35]
	v_pk_mul_f32 v[30:31], v[18:19], v[30:31]
	v_pk_mul_f32 v[34:35], v[54:55], v[4:5] op_sel_hi:[1,0]
	v_pk_mul_f32 v[30:31], v[30:31], v[50:51]
	v_pk_mul_f32 v[34:35], v[40:41], v[34:35]
	v_bfe_u32 v7, v23, 16, 1
	v_bfe_u32 v8, v22, 16, 1
	v_pk_mul_f32 v[34:35], v[34:35], v[52:53]
	v_add3_u32 v8, v22, v8, s39
	v_add3_u32 v7, v23, v7, s39
	v_bfe_u32 v12, v14, 16, 1
	v_bfe_u32 v16, v15, 16, 1
	v_bfe_u32 v22, v30, 16, 1
	v_bfe_u32 v23, v31, 16, 1
	v_bfe_u32 v3, v35, 16, 1
	v_bfe_u32 v4, v34, 16, 1
	v_add3_u32 v23, v31, v23, s39
	v_add3_u32 v22, v30, v22, s39
	v_add3_u32 v15, v15, v16, s39
	v_add3_u32 v12, v14, v12, s39
	v_add3_u32 v4, v34, v4, s39
	v_add3_u32 v3, v35, v3, s39
	v_lshrrev_b32_e32 v12, 16, v12
	v_lshrrev_b32_e32 v14, 16, v15
	v_lshrrev_b32_e32 v15, 16, v22
	v_lshrrev_b32_e32 v16, 16, v23
	v_and_or_b32 v53, v3, s36, v16
	v_and_or_b32 v52, v4, s36, v15
	v_and_or_b32 v51, v7, s36, v14
	v_and_or_b32 v50, v8, s36, v12
	v_or_b32_e32 v8, 3, v44
	global_store_dwordx4 v[10:11], v[50:53], off offset:3072
	v_mad_i64_i32 v[10:11], s[6:7], v8, s37, v[46:47]
	v_lshl_add_u64 v[10:11], v[10:11], 0, s[8:9]
	v_lshl_add_u64 v[10:11], v[10:11], 0, v[0:1]
	v_add_co_u32_e32 v10, vcc, s11, v10
	v_mov_b32_e32 v12, v9
	s_nop 0
	v_addc_co_u32_e32 v11, vcc, 0, v11, vcc
	s_waitcnt vmcnt(3)
	v_mov_b32_e32 v44, v88
	v_mov_b32_e32 v45, v89
	v_mov_b32_e32 v46, v90
	v_mov_b32_e32 v47, v91
	ds_read_b128 v[50:53], v155 offset:1536
	ds_read_b128 v[54:57], v155 offset:1552
	v_mov_b32_e32 v16, v5
	v_ashrrev_i32_e32 v9, 31, v8
	s_waitcnt lgkmcnt(1)
	v_mov_b32_e32 v10, v50
	v_mov_b32_e32 v11, v52
	v_mov_b32_e32 v52, v51
	v_pk_add_f32 v[10:11], v[32:33], v[10:11]
	v_pk_add_f32 v[14:15], v[24:25], v[52:53]
	v_pk_mul_f32 v[22:23], v[10:11], v[10:11]
	v_pk_mul_f32 v[24:25], v[14:15], v[14:15]
	s_waitcnt lgkmcnt(0)
	v_mov_b32_e32 v28, v54
	v_mov_b32_e32 v29, v56
	v_mov_b32_e32 v56, v55
	v_pk_add_f32 v[12:13], v[12:13], v[28:29]
	v_pk_add_f32 v[4:5], v[16:17], v[56:57]
	v_add_f32_e32 v3, v22, v24
	v_mov_b32_e32 v16, v4
	v_mov_b32_e32 v17, v12
	v_add_f32_e32 v3, v23, v3
	v_pk_mul_f32 v[16:17], v[16:17], v[16:17]
	v_add_f32_e32 v3, v25, v3
	v_mov_b32_e32 v28, v5
	v_mov_b32_e32 v29, v13
	v_add_f32_e32 v3, v17, v3
	v_pk_mul_f32 v[28:29], v[28:29], v[28:29]
	v_add_f32_e32 v3, v16, v3
	v_add_f32_e32 v3, v29, v3
	v_add_f32_e32 v3, v28, v3
	ds_bpermute_b32 v7, v48, v3
	s_waitcnt lgkmcnt(0)
	v_add_f32_e32 v3, v3, v7
	ds_bpermute_b32 v2, v2, v3
	s_waitcnt lgkmcnt(0)
	v_add_f32_e32 v2, v3, v2
	ds_bpermute_b32 v3, v6, v2
	s_waitcnt lgkmcnt(0)
	v_add_f32_e32 v6, v2, v3
	ds_bpermute_b32 v7, v26, v6
	s_waitcnt lgkmcnt(0)
	v_add_f32_e32 v6, v6, v7
	v_fmamk_f32 v6, v6, 0x3c000000, v156
	v_mul_f32_e32 v7, 0x4f800000, v6
	v_cmp_gt_f32_e32 vcc, s3, v6
	v_lshlrev_b32_e32 v3, 16, v45
	v_cndmask_b32_e32 v16, v6, v7, vcc
	v_sqrt_f32_e32 v22, v16
	v_lshlrev_b32_e32 v2, 16, v44
	v_and_b32_e32 v7, 0xffff0000, v45
	v_and_b32_e32 v6, 0xffff0000, v44
	v_add_u32_e32 v23, -1, v22
	v_fma_f32 v24, -v23, v22, v16
	v_cmp_ge_f32_e64 s[6:7], 0, v24
	v_add_u32_e32 v24, 1, v22
	v_lshlrev_b32_e32 v17, 16, v47
	v_cndmask_b32_e64 v23, v22, v23, s[6:7]
	v_fma_f32 v22, -v24, v22, v16
	v_cmp_lt_f32_e64 s[6:7], 0, v22
	s_nop 1
	v_cndmask_b32_e64 v22, v23, v24, s[6:7]
	v_mul_f32_e32 v23, 0x37800000, v22
	v_cndmask_b32_e32 v22, v22, v23, vcc
	v_cmp_class_f32_e32 vcc, v16, v157
	v_and_b32_e32 v23, 0xffff0000, v47
	s_nop 0
	v_cndmask_b32_e32 v24, v22, v16, vcc
	v_div_scale_f32 v25, s[6:7], v24, v24, 1.0
	v_rcp_f32_e32 v26, v25
	v_and_b32_e32 v22, 0xffff0000, v46
	v_lshlrev_b32_e32 v16, 16, v46
	v_fma_f32 v27, -v25, v26, 1.0
	v_fmac_f32_e32 v26, v27, v26
	v_div_scale_f32 v27, vcc, 1.0, v24, 1.0
	v_mul_f32_e32 v28, v27, v26
	v_fma_f32 v29, -v25, v28, v27
	v_fmac_f32_e32 v28, v29, v26
	v_fma_f32 v25, -v25, v28, v27
	v_div_fmas_f32 v25, v25, v26, v28
	v_div_fixup_f32 v24, v25, v24, 1.0
	v_pk_mul_f32 v[10:11], v[10:11], v[24:25] op_sel_hi:[1,0]
	v_pk_mul_f32 v[4:5], v[4:5], v[24:25] op_sel_hi:[1,0]
	v_pk_mul_f32 v[10:11], v[42:43], v[10:11]
	v_pk_mul_f32 v[4:5], v[40:41], v[4:5]
	v_pk_mul_f32 v[2:3], v[10:11], v[2:3]
	v_pk_mul_f32 v[10:11], v[14:15], v[24:25] op_sel_hi:[1,0]
	v_pk_mul_f32 v[4:5], v[4:5], v[22:23]
	v_pk_mul_f32 v[10:11], v[20:21], v[10:11]
	s_nop 0
	v_pk_mul_f32 v[6:7], v[10:11], v[6:7]
	v_pk_mul_f32 v[10:11], v[12:13], v[24:25] op_sel_hi:[1,0]
	v_bfe_u32 v12, v5, 16, 1
	v_bfe_u32 v13, v4, 16, 1
	v_add3_u32 v4, v4, v13, s39
	v_add3_u32 v5, v5, v12, s39
	v_bfe_u32 v12, v2, 16, 1
	v_bfe_u32 v13, v3, 16, 1
	v_pk_mul_f32 v[10:11], v[18:19], v[10:11]
	v_bfe_u32 v14, v7, 16, 1
	v_bfe_u32 v15, v6, 16, 1
	v_add3_u32 v3, v3, v13, s39
	v_add3_u32 v2, v2, v12, s39
	v_pk_mul_f32 v[10:11], v[10:11], v[16:17]
	v_add3_u32 v6, v6, v15, s39
	v_add3_u32 v7, v7, v14, s39
	v_lshrrev_b32_e32 v2, 16, v2
	v_lshrrev_b32_e32 v3, 16, v3
	v_bfe_u32 v14, v10, 16, 1
	v_bfe_u32 v15, v11, 16, 1
	v_and_or_b32 v3, v7, s36, v3
	v_and_or_b32 v2, v6, s36, v2
	v_lshlrev_b64 v[6:7], 12, v[8:9]
	v_add3_u32 v11, v11, v15, s39
	v_add3_u32 v10, v10, v14, s39
	v_lshl_add_u64 v[6:7], s[4:5], 0, v[6:7]
	v_lshrrev_b32_e32 v10, 16, v10
	v_lshrrev_b32_e32 v11, 16, v11
	v_lshl_add_u64 v[6:7], v[6:7], 0, s[8:9]
	v_and_or_b32 v5, v5, s36, v11
	v_and_or_b32 v4, v4, s36, v10
	v_lshl_add_u64 v[6:7], v[6:7], 0, v[0:1]
	global_store_dwordx4 v[6:7], v[2:5], off offset:3072
	s_branch .LBB0_1510
